# v7 + sample GEMM of the odd-layer input projection: fragment loads 8 k-steps (40 loads) deep instead of ~6 loads
# baseline (speedup 1.0000x reference)
; #define MFMA16(a, b, c) __builtin_amdgcn_mfma_f32_16x16x32_bf16((a), (b), (c), 0, 0, 0)
; #define SG_LOAD(kb_, buf_) do { _Pragma("unroll") for (int k4 = 0; k4 < 4; ++k4) { Af[buf_][k4] = *(const bf16x8*)(ap + 128 * (kb_) + 32 * k4); \
;                 _Pragma("unroll") for (int jn = 0; jn < NTW; ++jn) Bf[buf_][k4][jn] = *(const bf16x8*)(bp + (size_t)(16 * jn) * K + 128 * (kb_) + 32 * k4); } } while (0)
;     __device__ __forceinline__ Pre pre(int row, int col) const { return Pre{rstd32(rsqs + row * 32)}; }
;     __device__ __forceinline__ Pre pre(int row, int col) const { return Pre{rstd32(rsqs + row * 32)}; }
; __device__ __forceinline__ float rstd32(const float* p) {
;     f32x4 s = ((const f32x4*)p)[0];
; #pragma unroll
;     for (int i = 1; i < 8; ++i) s += ((const f32x4*)p)[i];
; template <class Epi, int N>
; __device__ __forceinline__ void sgemm16(Frame& F0, const bf16_t* A, const bf16_t* Bt, int K, const Epi& E) {
;     ...
;         typename Epi::Pre pre{};
;         if (eact) pre = E.pre(16 * F.xq + erow, slot * CW + 8 * ecg);
;         f32x4 acc[NTW];
; #pragma unroll
;         for (int jn = 0; jn < NTW; ++jn) acc[jn] = (f32x4){0.f, 0.f, 0.f, 0.f};
;         const bf16_t* ap = A16 + (size_t)fr * K + ksi * kslice + 8 * fq;
;         const bf16_t* bp = Bt + (size_t)(slot * CW + (ng * NTW) * 16 + fr) * K + ksi * kslice + 8 * fq;
;         {
;             bf16x8 Af[2][4], Bf[2][4][NTW];
;     ...
;             SG_LOAD(0, 0);
;             for (int kb = 0; kb < nkb; kb += 2) {
;                 if (kb + 1 < nkb) SG_LOAD(kb + 1, 1);
; #pragma unroll
;                 for (int k4 = 0; k4 < 4; ++k4)
; #pragma unroll
;                     for (int jn = 0; jn < NTW; ++jn) acc[jn] = MFMA16(Bf[0][k4][jn], Af[0][k4], acc[jn]);
;                 if (kb + 1 < nkb) {
;                     if (kb + 2 < nkb) SG_LOAD(kb + 2, 0);
; #pragma unroll
;                     for (int k4 = 0; k4 < 4; ++k4)
; #pragma unroll
;                         for (int jn = 0; jn < NTW; ++jn) acc[jn] = MFMA16(Bf[1][k4][jn], Af[1][k4], acc[jn]);
;                 }
;             }
.LBB0_666:
	v_mov_b32_e32 v8, 0
	s_and_saveexec_b64 s[10:11], s[8:9]
	s_cbranch_execz .LsgA_a
	global_load_dwordx4 v[28:31], v[4:5], off
	global_load_dwordx4 v[32:35], v[4:5], off offset:16
	global_load_dwordx4 v[36:39], v[4:5], off offset:32
	global_load_dwordx4 v[40:43], v[4:5], off offset:48
	global_load_dwordx4 v[44:47], v[4:5], off offset:64
	global_load_dwordx4 v[48:51], v[4:5], off offset:80
	global_load_dwordx4 v[52:55], v[4:5], off offset:96
	global_load_dwordx4 v[56:59], v[4:5], off offset:112
.LsgA_a:
	s_or_b64 exec, exec, s[10:11]
	v_add_u32_e32 v248, v22, v23
	v_ashrrev_i32_e32 v249, 31, v248
	v_lshlrev_b64 v[248:249], 11, v[248:249]
	v_lshl_add_u64 v[240:241], v[2:3], 0, v[248:249]
	v_add_co_u32_e32 v242, vcc, 0x8000, v240
	s_nop 1
	v_addc_co_u32_e32 v243, vcc, 0, v241, vcc
	v_add_co_u32_e32 v244, vcc, 0x10000, v240
	s_nop 1
	v_addc_co_u32_e32 v245, vcc, 0, v241, vcc
	v_add_co_u32_e32 v246, vcc, 0x18000, v240
	s_nop 1
	v_addc_co_u32_e32 v247, vcc, 0, v241, vcc
	global_load_dwordx4 v[60:63], v[0:1], off
	global_load_dwordx4 v[64:67], v[240:241], off
	global_load_dwordx4 v[68:71], v[242:243], off
	global_load_dwordx4 v[72:75], v[244:245], off
	global_load_dwordx4 v[76:79], v[246:247], off
	global_load_dwordx4 v[80:83], v[0:1], off offset:64
	global_load_dwordx4 v[84:87], v[240:241], off offset:64
	global_load_dwordx4 v[88:91], v[242:243], off offset:64
	global_load_dwordx4 v[92:95], v[244:245], off offset:64
	global_load_dwordx4 v[96:99], v[246:247], off offset:64
	global_load_dwordx4 v[100:103], v[0:1], off offset:128
	global_load_dwordx4 v[104:107], v[240:241], off offset:128
	global_load_dwordx4 v[108:111], v[242:243], off offset:128
	global_load_dwordx4 v[112:115], v[244:245], off offset:128
	global_load_dwordx4 v[116:119], v[246:247], off offset:128
	global_load_dwordx4 v[120:123], v[0:1], off offset:192
	global_load_dwordx4 v[124:127], v[240:241], off offset:192
	global_load_dwordx4 v[128:131], v[242:243], off offset:192
	global_load_dwordx4 v[132:135], v[244:245], off offset:192
	global_load_dwordx4 v[136:139], v[246:247], off offset:192
	global_load_dwordx4 v[140:143], v[0:1], off offset:256
	global_load_dwordx4 v[144:147], v[240:241], off offset:256
	global_load_dwordx4 v[148:151], v[242:243], off offset:256
	global_load_dwordx4 v[152:155], v[244:245], off offset:256
	global_load_dwordx4 v[156:159], v[246:247], off offset:256
	global_load_dwordx4 v[160:163], v[0:1], off offset:320
	global_load_dwordx4 v[164:167], v[240:241], off offset:320
	global_load_dwordx4 v[168:171], v[242:243], off offset:320
	global_load_dwordx4 v[172:175], v[244:245], off offset:320
	global_load_dwordx4 v[176:179], v[246:247], off offset:320
	global_load_dwordx4 v[180:183], v[0:1], off offset:384
	global_load_dwordx4 v[184:187], v[240:241], off offset:384
	global_load_dwordx4 v[188:191], v[242:243], off offset:384
	global_load_dwordx4 v[192:195], v[244:245], off offset:384
	global_load_dwordx4 v[196:199], v[246:247], off offset:384
	global_load_dwordx4 v[202:205], v[0:1], off offset:448
	global_load_dwordx4 v[206:209], v[240:241], off offset:448
	global_load_dwordx4 v[210:213], v[242:243], off offset:448
	global_load_dwordx4 v[214:217], v[244:245], off offset:448
	global_load_dwordx4 v[218:221], v[246:247], off offset:448
	s_waitcnt vmcnt(38)
	v_mfma_f32_16x16x32_bf16 v[224:227], v[64:67], v[60:63], 0
	s_waitcnt vmcnt(37)
	v_mfma_f32_16x16x32_bf16 v[228:231], v[68:71], v[60:63], 0
	s_waitcnt vmcnt(36)
	v_mfma_f32_16x16x32_bf16 v[232:235], v[72:75], v[60:63], 0
	s_waitcnt vmcnt(35)
	v_mfma_f32_16x16x32_bf16 v[236:239], v[76:79], v[60:63], 0
	global_load_dwordx4 v[60:63], v[0:1], off offset:512
	global_load_dwordx4 v[64:67], v[240:241], off offset:512
	global_load_dwordx4 v[68:71], v[242:243], off offset:512
	global_load_dwordx4 v[72:75], v[244:245], off offset:512
	global_load_dwordx4 v[76:79], v[246:247], off offset:512
	s_waitcnt vmcnt(38)
	v_mfma_f32_16x16x32_bf16 v[224:227], v[84:87], v[80:83], v[224:227]
	s_waitcnt vmcnt(37)
	v_mfma_f32_16x16x32_bf16 v[228:231], v[88:91], v[80:83], v[228:231]
	s_waitcnt vmcnt(36)
	v_mfma_f32_16x16x32_bf16 v[232:235], v[92:95], v[80:83], v[232:235]
	s_waitcnt vmcnt(35)
	v_mfma_f32_16x16x32_bf16 v[236:239], v[96:99], v[80:83], v[236:239]
	global_load_dwordx4 v[80:83], v[0:1], off offset:576
	global_load_dwordx4 v[84:87], v[240:241], off offset:576
	global_load_dwordx4 v[88:91], v[242:243], off offset:576
	global_load_dwordx4 v[92:95], v[244:245], off offset:576
	global_load_dwordx4 v[96:99], v[246:247], off offset:576
	s_waitcnt vmcnt(38)
	v_mfma_f32_16x16x32_bf16 v[224:227], v[104:107], v[100:103], v[224:227]
	s_waitcnt vmcnt(37)
	v_mfma_f32_16x16x32_bf16 v[228:231], v[108:111], v[100:103], v[228:231]
	s_waitcnt vmcnt(36)
	v_mfma_f32_16x16x32_bf16 v[232:235], v[112:115], v[100:103], v[232:235]
	s_waitcnt vmcnt(35)
	v_mfma_f32_16x16x32_bf16 v[236:239], v[116:119], v[100:103], v[236:239]
	global_load_dwordx4 v[100:103], v[0:1], off offset:640
	global_load_dwordx4 v[104:107], v[240:241], off offset:640
	global_load_dwordx4 v[108:111], v[242:243], off offset:640
	global_load_dwordx4 v[112:115], v[244:245], off offset:640
	global_load_dwordx4 v[116:119], v[246:247], off offset:640
	s_waitcnt vmcnt(38)
	v_mfma_f32_16x16x32_bf16 v[224:227], v[124:127], v[120:123], v[224:227]
	s_waitcnt vmcnt(37)
	v_mfma_f32_16x16x32_bf16 v[228:231], v[128:131], v[120:123], v[228:231]
	s_waitcnt vmcnt(36)
	v_mfma_f32_16x16x32_bf16 v[232:235], v[132:135], v[120:123], v[232:235]
	s_waitcnt vmcnt(35)
; #define MFMA16(a, b, c) __builtin_amdgcn_mfma_f32_16x16x32_bf16((a), (b), (c), 0, 0, 0)
; #define SG_LOAD(kb_, buf_) do { _Pragma("unroll") for (int k4 = 0; k4 < 4; ++k4) { Af[buf_][k4] = *(const bf16x8*)(ap + 128 * (kb_) + 32 * k4); \
;                 _Pragma("unroll") for (int jn = 0; jn < NTW; ++jn) Bf[buf_][k4][jn] = *(const bf16x8*)(bp + (size_t)(16 * jn) * K + 128 * (kb_) + 32 * k4); } } while (0)
; template <class Epi, int N>
; __device__ __forceinline__ void sgemm16(Frame& F0, const bf16_t* A, const bf16_t* Bt, int K, const Epi& E) {
;     ...
;             for (int kb = 0; kb < nkb; kb += 2) {
;                 if (kb + 1 < nkb) SG_LOAD(kb + 1, 1);
; #pragma unroll
;                 for (int k4 = 0; k4 < 4; ++k4)
; #pragma unroll
;                     for (int jn = 0; jn < NTW; ++jn) acc[jn] = MFMA16(Bf[0][k4][jn], Af[0][k4], acc[jn]);
;                 if (kb + 1 < nkb) {
;                     if (kb + 2 < nkb) SG_LOAD(kb + 2, 0);
; #pragma unroll
;                     for (int k4 = 0; k4 < 4; ++k4)
; #pragma unroll
;                         for (int jn = 0; jn < NTW; ++jn) acc[jn] = MFMA16(Bf[1][k4][jn], Af[1][k4], acc[jn]);
;                 }
;             }
	v_mfma_f32_16x16x32_bf16 v[236:239], v[136:139], v[120:123], v[236:239]
	global_load_dwordx4 v[120:123], v[0:1], off offset:704
	global_load_dwordx4 v[124:127], v[240:241], off offset:704
	global_load_dwordx4 v[128:131], v[242:243], off offset:704
	global_load_dwordx4 v[132:135], v[244:245], off offset:704
	global_load_dwordx4 v[136:139], v[246:247], off offset:704
	s_waitcnt vmcnt(38)
	v_mfma_f32_16x16x32_bf16 v[224:227], v[144:147], v[140:143], v[224:227]
	s_waitcnt vmcnt(37)
	v_mfma_f32_16x16x32_bf16 v[228:231], v[148:151], v[140:143], v[228:231]
	s_waitcnt vmcnt(36)
	v_mfma_f32_16x16x32_bf16 v[232:235], v[152:155], v[140:143], v[232:235]
	s_waitcnt vmcnt(35)
	v_mfma_f32_16x16x32_bf16 v[236:239], v[156:159], v[140:143], v[236:239]
	global_load_dwordx4 v[140:143], v[0:1], off offset:768
	global_load_dwordx4 v[144:147], v[240:241], off offset:768
	global_load_dwordx4 v[148:151], v[242:243], off offset:768
	global_load_dwordx4 v[152:155], v[244:245], off offset:768
	global_load_dwordx4 v[156:159], v[246:247], off offset:768
	s_waitcnt vmcnt(38)
	v_mfma_f32_16x16x32_bf16 v[224:227], v[164:167], v[160:163], v[224:227]
	s_waitcnt vmcnt(37)
	v_mfma_f32_16x16x32_bf16 v[228:231], v[168:171], v[160:163], v[228:231]
	s_waitcnt vmcnt(36)
	v_mfma_f32_16x16x32_bf16 v[232:235], v[172:175], v[160:163], v[232:235]
	s_waitcnt vmcnt(35)
	v_mfma_f32_16x16x32_bf16 v[236:239], v[176:179], v[160:163], v[236:239]
	global_load_dwordx4 v[160:163], v[0:1], off offset:832
	global_load_dwordx4 v[164:167], v[240:241], off offset:832
	global_load_dwordx4 v[168:171], v[242:243], off offset:832
	global_load_dwordx4 v[172:175], v[244:245], off offset:832
	global_load_dwordx4 v[176:179], v[246:247], off offset:832
	s_waitcnt vmcnt(38)
	v_mfma_f32_16x16x32_bf16 v[224:227], v[184:187], v[180:183], v[224:227]
	s_waitcnt vmcnt(37)
	v_mfma_f32_16x16x32_bf16 v[228:231], v[188:191], v[180:183], v[228:231]
	s_waitcnt vmcnt(36)
	v_mfma_f32_16x16x32_bf16 v[232:235], v[192:195], v[180:183], v[232:235]
	s_waitcnt vmcnt(35)
	v_mfma_f32_16x16x32_bf16 v[236:239], v[196:199], v[180:183], v[236:239]
	global_load_dwordx4 v[180:183], v[0:1], off offset:896
	global_load_dwordx4 v[184:187], v[240:241], off offset:896
	global_load_dwordx4 v[188:191], v[242:243], off offset:896
	global_load_dwordx4 v[192:195], v[244:245], off offset:896
	global_load_dwordx4 v[196:199], v[246:247], off offset:896
	s_waitcnt vmcnt(38)
	v_mfma_f32_16x16x32_bf16 v[224:227], v[206:209], v[202:205], v[224:227]
	s_waitcnt vmcnt(37)
	v_mfma_f32_16x16x32_bf16 v[228:231], v[210:213], v[202:205], v[228:231]
	s_waitcnt vmcnt(36)
	v_mfma_f32_16x16x32_bf16 v[232:235], v[214:217], v[202:205], v[232:235]
	s_waitcnt vmcnt(35)
	v_mfma_f32_16x16x32_bf16 v[236:239], v[218:221], v[202:205], v[236:239]
	global_load_dwordx4 v[202:205], v[0:1], off offset:960
	global_load_dwordx4 v[206:209], v[240:241], off offset:960
	global_load_dwordx4 v[210:213], v[242:243], off offset:960
	global_load_dwordx4 v[214:217], v[244:245], off offset:960
	global_load_dwordx4 v[218:221], v[246:247], off offset:960
	s_waitcnt vmcnt(38)
	v_mfma_f32_16x16x32_bf16 v[224:227], v[64:67], v[60:63], v[224:227]
	s_waitcnt vmcnt(37)
	v_mfma_f32_16x16x32_bf16 v[228:231], v[68:71], v[60:63], v[228:231]
	s_waitcnt vmcnt(36)
	v_mfma_f32_16x16x32_bf16 v[232:235], v[72:75], v[60:63], v[232:235]
	s_waitcnt vmcnt(35)
	v_mfma_f32_16x16x32_bf16 v[236:239], v[76:79], v[60:63], v[236:239]
	s_waitcnt vmcnt(33)
	v_mfma_f32_16x16x32_bf16 v[224:227], v[84:87], v[80:83], v[224:227]
	s_waitcnt vmcnt(32)
	v_mfma_f32_16x16x32_bf16 v[228:231], v[88:91], v[80:83], v[228:231]
	s_waitcnt vmcnt(31)
	v_mfma_f32_16x16x32_bf16 v[232:235], v[92:95], v[80:83], v[232:235]
	s_waitcnt vmcnt(30)
	v_mfma_f32_16x16x32_bf16 v[236:239], v[96:99], v[80:83], v[236:239]
	s_waitcnt vmcnt(28)
	v_mfma_f32_16x16x32_bf16 v[224:227], v[104:107], v[100:103], v[224:227]
	s_waitcnt vmcnt(27)
	v_mfma_f32_16x16x32_bf16 v[228:231], v[108:111], v[100:103], v[228:231]
	s_waitcnt vmcnt(26)
	v_mfma_f32_16x16x32_bf16 v[232:235], v[112:115], v[100:103], v[232:235]
	s_waitcnt vmcnt(25)
	v_mfma_f32_16x16x32_bf16 v[236:239], v[116:119], v[100:103], v[236:239]
	s_waitcnt vmcnt(23)
	v_mfma_f32_16x16x32_bf16 v[224:227], v[124:127], v[120:123], v[224:227]
	s_waitcnt vmcnt(22)
	v_mfma_f32_16x16x32_bf16 v[228:231], v[128:131], v[120:123], v[228:231]
	s_waitcnt vmcnt(21)
	v_mfma_f32_16x16x32_bf16 v[232:235], v[132:135], v[120:123], v[232:235]
	s_waitcnt vmcnt(20)
	v_mfma_f32_16x16x32_bf16 v[236:239], v[136:139], v[120:123], v[236:239]
	s_waitcnt vmcnt(18)
	v_mfma_f32_16x16x32_bf16 v[224:227], v[144:147], v[140:143], v[224:227]
	s_waitcnt vmcnt(17)
	v_mfma_f32_16x16x32_bf16 v[228:231], v[148:151], v[140:143], v[228:231]
	s_waitcnt vmcnt(16)
	v_mfma_f32_16x16x32_bf16 v[232:235], v[152:155], v[140:143], v[232:235]
	s_waitcnt vmcnt(15)
	v_mfma_f32_16x16x32_bf16 v[236:239], v[156:159], v[140:143], v[236:239]
	s_waitcnt vmcnt(13)
	v_mfma_f32_16x16x32_bf16 v[224:227], v[164:167], v[160:163], v[224:227]
	s_waitcnt vmcnt(12)
	v_mfma_f32_16x16x32_bf16 v[228:231], v[168:171], v[160:163], v[228:231]
	s_waitcnt vmcnt(11)
	v_mfma_f32_16x16x32_bf16 v[232:235], v[172:175], v[160:163], v[232:235]
	s_waitcnt vmcnt(10)
	v_mfma_f32_16x16x32_bf16 v[236:239], v[176:179], v[160:163], v[236:239]
	s_waitcnt vmcnt(8)
	v_mfma_f32_16x16x32_bf16 v[224:227], v[184:187], v[180:183], v[224:227]
	s_waitcnt vmcnt(7)
	v_mfma_f32_16x16x32_bf16 v[228:231], v[188:191], v[180:183], v[228:231]
	s_waitcnt vmcnt(6)
	v_mfma_f32_16x16x32_bf16 v[232:235], v[192:195], v[180:183], v[232:235]
	s_waitcnt vmcnt(5)
	v_mfma_f32_16x16x32_bf16 v[236:239], v[196:199], v[180:183], v[236:239]
	s_waitcnt vmcnt(3)
	v_mfma_f32_16x16x32_bf16 v[224:227], v[206:209], v[202:205], v[224:227]
	s_waitcnt vmcnt(2)
	v_mfma_f32_16x16x32_bf16 v[228:231], v[210:213], v[202:205], v[228:231]
	s_waitcnt vmcnt(1)
	v_mfma_f32_16x16x32_bf16 v[232:235], v[214:217], v[202:205], v[232:235]
	s_waitcnt vmcnt(0)
	v_mfma_f32_16x16x32_bf16 v[236:239], v[218:221], v[202:205], v[236:239]
	s_and_saveexec_b64 s[10:11], s[8:9]
	s_cbranch_execz .LsgA_b
; #define LAS __attribute__((address_space(3)))
; #define LDS_BARRIER() asm volatile("s_waitcnt lgkmcnt(0)\n\ts_barrier" ::: "memory")
;     __device__ __forceinline__ Pre pre(int row, int col) const { return Pre{rstd32(rsqs + row * 32)}; }
; __device__ __forceinline__ float rstd32(const float* p) {
;     f32x4 s = ((const f32x4*)p)[0];
; #pragma unroll
;     for (int i = 1; i < 8; ++i) s += ((const f32x4*)p)[i];
;     return rsqrtf(((s[0] + s[1]) + (s[2] + s[3])) * (1.0f / D) + EPS);
; }
; template <class Epi, int N>
; __device__ __forceinline__ void sgemm16(Frame& F0, const bf16_t* A, const bf16_t* Bt, int K, const Epi& E) {
;     ...
;         for (int jn = 0; jn < NTW; ++jn) *(LAS f32x4*)(lds + ((size_t)((ksi * 16 + fr) * CW + (ng * NTW + jn) * 16 + 4 * fq)) * 4) = acc[jn];
;         LDS_BARRIER();
;         if (eact) {
;             f32x4 s0 = (f32x4){0.f, 0.f, 0.f, 0.f}, s1 = s0;
; #pragma unroll
;             for (int kk = 0; kk < KS; ++kk) { const LAS f32x4* p = (const LAS f32x4*)(lds + ((size_t)((kk * 16 + erow) * CW + 8 * ecg)) * 4); s0 += p[0]; s1 += p[1]; }
;             E(16 * F.xq + erow, slot, slot * CW + 8 * ecg, s0, s1, pre);
;         }
;         LDS_BARRIER();
;     }
; }
;     __device__ __forceinline__ Pre pre(int row, int col) const { return Pre{rstd32(rsqs + row * 32)}; }
;     __device__ __forceinline__ void operator()(int row, int strip, int col, f32x4 s0, f32x4 s1, const Pre& p) const {
;         const int oc0 = mode == 0 ? src_even(col) : src_odd(col), oc1 = mode == 0 ? src_even(col + 4) : src_odd(col + 4);
;         float* q = SZ + (size_t)row * ldz; *(f32x4*)(q + oc0) = s0 * p.rs; *(f32x4*)(q + oc1) = s1 * p.rs;
	s_mov_b32 s0, 0x800000
	v_pk_add_f32 v[30:31], v[30:31], v[34:35]
	v_pk_add_f32 v[28:29], v[28:29], v[32:33]
	v_pk_add_f32 v[30:31], v[30:31], v[38:39]
	v_pk_add_f32 v[28:29], v[28:29], v[36:37]
	v_pk_add_f32 v[30:31], v[30:31], v[42:43]
	v_pk_add_f32 v[28:29], v[28:29], v[40:41]
	v_pk_add_f32 v[30:31], v[30:31], v[46:47]
	v_pk_add_f32 v[28:29], v[28:29], v[44:45]
	v_pk_add_f32 v[30:31], v[30:31], v[50:51]
	v_pk_add_f32 v[28:29], v[28:29], v[48:49]
	v_pk_add_f32 v[30:31], v[30:31], v[54:55]
	v_pk_add_f32 v[28:29], v[28:29], v[52:53]
	v_pk_add_f32 v[30:31], v[30:31], v[58:59]
	v_pk_add_f32 v[28:29], v[28:29], v[56:57]
	s_nop 0
	v_pk_mov_b32 v[32:33], v[28:29], v[30:31] op_sel:[1,0]
	v_mov_b32_e32 v29, v31
	v_pk_add_f32 v[28:29], v[32:33], v[28:29]
	s_nop 0
	v_add_f32_e32 v8, v28, v29
	v_mov_b32_e32 v34, 0x358637bd
	v_fmamk_f32 v8, v8, 0x3a800000, v34
	v_cmp_gt_f32_e32 vcc, s0, v8
	v_mul_f32_e32 v34, 0x4b800000, v8
	s_nop 0
	v_cndmask_b32_e32 v8, v8, v34, vcc
	v_rsq_f32_e32 v8, v8
	s_nop 0
	v_mul_f32_e32 v34, 0x45800000, v8
	v_cndmask_b32_e32 v8, v8, v34, vcc
.LsgA_b:
	s_or_b64 exec, exec, s[10:11]
	s_nop 7
	ds_write_b128 v25, v[224:227]
	ds_write_b128 v25, v[228:231] offset:64
	ds_write_b128 v25, v[232:235] offset:128
	ds_write_b128 v25, v[236:239] offset:192
	s_waitcnt lgkmcnt(0)
	s_barrier
	s_and_saveexec_b64 s[10:11], s[8:9]
	s_cbranch_execz .LBB0_665
	ds_read_b128 v[10:13], v26
	ds_read_b128 v[14:17], v26 offset:16
	s_waitcnt lgkmcnt(0)
	v_pk_add_f32 v[28:29], v[12:13], 0 op_sel_hi:[1,0]
	v_pk_add_f32 v[30:31], v[10:11], 0 op_sel_hi:[1,0]
	ds_read_b128 v[10:13], v26 offset:16384
	v_pk_add_f32 v[14:15], v[14:15], 0 op_sel_hi:[1,0]
	v_pk_add_f32 v[16:17], v[16:17], 0 op_sel_hi:[1,0]
	s_waitcnt lgkmcnt(0)
	v_pk_add_f32 v[28:29], v[28:29], v[12:13]
	v_pk_add_f32 v[30:31], v[30:31], v[10:11]
	ds_read_b128 v[10:13], v26 offset:16400
	s_waitcnt lgkmcnt(0)
	v_pk_add_f32 v[14:15], v[14:15], v[10:11]
	v_add_u32_e32 v10, v18, v23
	v_ashrrev_i32_e32 v10, 2, v10
	v_and_b32_e32 v10, 0xffffffc0, v10
	v_add_u32_e32 v32, v10, v19
	v_add_u32_e32 v34, v20, v10
	v_ashrrev_i32_e32 v33, 31, v32
	v_pk_add_f32 v[16:17], v[16:17], v[12:13]
	v_pk_mul_f32 v[12:13], v[8:9], v[28:29] op_sel_hi:[0,1]
	v_pk_mul_f32 v[10:11], v[8:9], v[30:31] op_sel_hi:[0,1]
	v_lshl_add_u64 v[28:29], v[32:33], 2, v[6:7]
	v_ashrrev_i32_e32 v35, 31, v34
	global_store_dwordx4 v[28:29], v[10:13], off
	s_nop 1
	v_pk_mul_f32 v[12:13], v[8:9], v[16:17] op_sel_hi:[0,1]
	v_pk_mul_f32 v[10:11], v[8:9], v[14:15] op_sel_hi:[0,1]
	v_lshl_add_u64 v[14:15], v[34:35], 2, v[6:7]
	global_store_dwordx4 v[14:15], v[10:13], off
	s_branch .LBB0_665

; #define MFMA16(a, b, c) __builtin_amdgcn_mfma_f32_16x16x32_bf16((a), (b), (c), 0, 0, 0)
; #define SG_LOAD(kb_, buf_) do { _Pragma("unroll") for (int k4 = 0; k4 < 4; ++k4) { Af[buf_][k4] = *(const bf16x8*)(ap + 128 * (kb_) + 32 * k4); \
;                 _Pragma("unroll") for (int jn = 0; jn < NTW; ++jn) Bf[buf_][k4][jn] = *(const bf16x8*)(bp + (size_t)(16 * jn) * K + 128 * (kb_) + 32 * k4); } } while (0)
;     __device__ __forceinline__ Pre pre(int row, int col) const { return Pre{rstd32(rsqs + row * 32)}; }
;     __device__ __forceinline__ Pre pre(int row, int col) const { return Pre{rstd32(rsqs + row * 32)}; }
; __device__ __forceinline__ float rstd32(const float* p) {
;     f32x4 s = ((const f32x4*)p)[0];
; #pragma unroll
;     for (int i = 1; i < 8; ++i) s += ((const f32x4*)p)[i];
; template <class Epi, int N>
; __device__ __forceinline__ void sgemm16(Frame& F0, const bf16_t* A, const bf16_t* Bt, int K, const Epi& E) {
;     ...
;         typename Epi::Pre pre{};
;         if (eact) pre = E.pre(16 * F.xq + erow, slot * CW + 8 * ecg);
;         f32x4 acc[NTW];
; #pragma unroll
;         for (int jn = 0; jn < NTW; ++jn) acc[jn] = (f32x4){0.f, 0.f, 0.f, 0.f};
;         const bf16_t* ap = A16 + (size_t)fr * K + ksi * kslice + 8 * fq;
;         const bf16_t* bp = Bt + (size_t)(slot * CW + (ng * NTW) * 16 + fr) * K + ksi * kslice + 8 * fq;
;         {
;             bf16x8 Af[2][4], Bf[2][4][NTW];
;     ...
;             SG_LOAD(0, 0);
;             for (int kb = 0; kb < nkb; kb += 2) {
;                 if (kb + 1 < nkb) SG_LOAD(kb + 1, 1);
; #pragma unroll
;                 for (int k4 = 0; k4 < 4; ++k4)
; #pragma unroll
;                     for (int jn = 0; jn < NTW; ++jn) acc[jn] = MFMA16(Bf[0][k4][jn], Af[0][k4], acc[jn]);
;                 if (kb + 1 < nkb) {
;                     if (kb + 2 < nkb) SG_LOAD(kb + 2, 0);
; #pragma unroll
;                     for (int k4 = 0; k4 < 4; ++k4)
; #pragma unroll
;                         for (int jn = 0; jn < NTW; ++jn) acc[jn] = MFMA16(Bf[1][k4][jn], Af[1][k4], acc[jn]);
;                 }
;             }
.LBB0_790:
	v_mov_b32_e32 v8, 0
	s_and_saveexec_b64 s[2:3], s[6:7]
	s_cbranch_execz .LsgB_a
	global_load_dwordx4 v[28:31], v[4:5], off
	global_load_dwordx4 v[32:35], v[4:5], off offset:16
	global_load_dwordx4 v[36:39], v[4:5], off offset:32
	global_load_dwordx4 v[40:43], v[4:5], off offset:48
	global_load_dwordx4 v[44:47], v[4:5], off offset:64
	global_load_dwordx4 v[48:51], v[4:5], off offset:80
	global_load_dwordx4 v[52:55], v[4:5], off offset:96
	global_load_dwordx4 v[56:59], v[4:5], off offset:112
.LsgB_a:
	s_or_b64 exec, exec, s[2:3]
	v_add_u32_e32 v248, v22, v23
	v_ashrrev_i32_e32 v249, 31, v248
	v_lshlrev_b64 v[248:249], 11, v[248:249]
	v_lshl_add_u64 v[240:241], v[2:3], 0, v[248:249]
	v_add_co_u32_e32 v242, vcc, 0x8000, v240
	s_nop 1
	v_addc_co_u32_e32 v243, vcc, 0, v241, vcc
	v_add_co_u32_e32 v244, vcc, 0x10000, v240
	s_nop 1
	v_addc_co_u32_e32 v245, vcc, 0, v241, vcc
	v_add_co_u32_e32 v246, vcc, 0x18000, v240
	s_nop 1
	v_addc_co_u32_e32 v247, vcc, 0, v241, vcc
	global_load_dwordx4 v[60:63], v[0:1], off
	global_load_dwordx4 v[64:67], v[240:241], off
	global_load_dwordx4 v[68:71], v[242:243], off
	global_load_dwordx4 v[72:75], v[244:245], off
	global_load_dwordx4 v[76:79], v[246:247], off
	global_load_dwordx4 v[80:83], v[0:1], off offset:64
	global_load_dwordx4 v[84:87], v[240:241], off offset:64
	global_load_dwordx4 v[88:91], v[242:243], off offset:64
	global_load_dwordx4 v[92:95], v[244:245], off offset:64
	global_load_dwordx4 v[96:99], v[246:247], off offset:64
	global_load_dwordx4 v[100:103], v[0:1], off offset:128
	global_load_dwordx4 v[104:107], v[240:241], off offset:128
	global_load_dwordx4 v[108:111], v[242:243], off offset:128
	global_load_dwordx4 v[112:115], v[244:245], off offset:128
	global_load_dwordx4 v[116:119], v[246:247], off offset:128
	global_load_dwordx4 v[120:123], v[0:1], off offset:192
	global_load_dwordx4 v[124:127], v[240:241], off offset:192
	global_load_dwordx4 v[128:131], v[242:243], off offset:192
	global_load_dwordx4 v[132:135], v[244:245], off offset:192
	global_load_dwordx4 v[136:139], v[246:247], off offset:192
	global_load_dwordx4 v[140:143], v[0:1], off offset:256
	global_load_dwordx4 v[144:147], v[240:241], off offset:256
	global_load_dwordx4 v[148:151], v[242:243], off offset:256
	global_load_dwordx4 v[152:155], v[244:245], off offset:256
	global_load_dwordx4 v[156:159], v[246:247], off offset:256
	global_load_dwordx4 v[160:163], v[0:1], off offset:320
	global_load_dwordx4 v[164:167], v[240:241], off offset:320
	global_load_dwordx4 v[168:171], v[242:243], off offset:320
	global_load_dwordx4 v[172:175], v[244:245], off offset:320
	global_load_dwordx4 v[176:179], v[246:247], off offset:320
	global_load_dwordx4 v[180:183], v[0:1], off offset:384
	global_load_dwordx4 v[184:187], v[240:241], off offset:384
	global_load_dwordx4 v[188:191], v[242:243], off offset:384
	global_load_dwordx4 v[192:195], v[244:245], off offset:384
	global_load_dwordx4 v[196:199], v[246:247], off offset:384
	global_load_dwordx4 v[202:205], v[0:1], off offset:448
	global_load_dwordx4 v[206:209], v[240:241], off offset:448
	global_load_dwordx4 v[210:213], v[242:243], off offset:448
	global_load_dwordx4 v[214:217], v[244:245], off offset:448
	global_load_dwordx4 v[218:221], v[246:247], off offset:448
	s_waitcnt vmcnt(38)
	v_mfma_f32_16x16x32_bf16 v[224:227], v[64:67], v[60:63], 0
	s_waitcnt vmcnt(37)
	v_mfma_f32_16x16x32_bf16 v[228:231], v[68:71], v[60:63], 0
	s_waitcnt vmcnt(36)
	v_mfma_f32_16x16x32_bf16 v[232:235], v[72:75], v[60:63], 0
	s_waitcnt vmcnt(35)
	v_mfma_f32_16x16x32_bf16 v[236:239], v[76:79], v[60:63], 0
	global_load_dwordx4 v[60:63], v[0:1], off offset:512
	global_load_dwordx4 v[64:67], v[240:241], off offset:512
	global_load_dwordx4 v[68:71], v[242:243], off offset:512
	global_load_dwordx4 v[72:75], v[244:245], off offset:512
	global_load_dwordx4 v[76:79], v[246:247], off offset:512
	s_waitcnt vmcnt(38)
	v_mfma_f32_16x16x32_bf16 v[224:227], v[84:87], v[80:83], v[224:227]
	s_waitcnt vmcnt(37)
	v_mfma_f32_16x16x32_bf16 v[228:231], v[88:91], v[80:83], v[228:231]
	s_waitcnt vmcnt(36)
	v_mfma_f32_16x16x32_bf16 v[232:235], v[92:95], v[80:83], v[232:235]
	s_waitcnt vmcnt(35)
	v_mfma_f32_16x16x32_bf16 v[236:239], v[96:99], v[80:83], v[236:239]
	global_load_dwordx4 v[80:83], v[0:1], off offset:576
	global_load_dwordx4 v[84:87], v[240:241], off offset:576
	global_load_dwordx4 v[88:91], v[242:243], off offset:576
	global_load_dwordx4 v[92:95], v[244:245], off offset:576
	global_load_dwordx4 v[96:99], v[246:247], off offset:576
	s_waitcnt vmcnt(38)
	v_mfma_f32_16x16x32_bf16 v[224:227], v[104:107], v[100:103], v[224:227]
	s_waitcnt vmcnt(37)
	v_mfma_f32_16x16x32_bf16 v[228:231], v[108:111], v[100:103], v[228:231]
	s_waitcnt vmcnt(36)
	v_mfma_f32_16x16x32_bf16 v[232:235], v[112:115], v[100:103], v[232:235]
	s_waitcnt vmcnt(35)
	v_mfma_f32_16x16x32_bf16 v[236:239], v[116:119], v[100:103], v[236:239]
	global_load_dwordx4 v[100:103], v[0:1], off offset:640
	global_load_dwordx4 v[104:107], v[240:241], off offset:640
	global_load_dwordx4 v[108:111], v[242:243], off offset:640
	global_load_dwordx4 v[112:115], v[244:245], off offset:640
	global_load_dwordx4 v[116:119], v[246:247], off offset:640
	s_waitcnt vmcnt(38)
	v_mfma_f32_16x16x32_bf16 v[224:227], v[124:127], v[120:123], v[224:227]
	s_waitcnt vmcnt(37)
	v_mfma_f32_16x16x32_bf16 v[228:231], v[128:131], v[120:123], v[228:231]
	s_waitcnt vmcnt(36)
	v_mfma_f32_16x16x32_bf16 v[232:235], v[132:135], v[120:123], v[232:235]
	s_waitcnt vmcnt(35)
; #define MFMA16(a, b, c) __builtin_amdgcn_mfma_f32_16x16x32_bf16((a), (b), (c), 0, 0, 0)
; #define SG_LOAD(kb_, buf_) do { _Pragma("unroll") for (int k4 = 0; k4 < 4; ++k4) { Af[buf_][k4] = *(const bf16x8*)(ap + 128 * (kb_) + 32 * k4); \
;                 _Pragma("unroll") for (int jn = 0; jn < NTW; ++jn) Bf[buf_][k4][jn] = *(const bf16x8*)(bp + (size_t)(16 * jn) * K + 128 * (kb_) + 32 * k4); } } while (0)
; template <class Epi, int N>
; __device__ __forceinline__ void sgemm16(Frame& F0, const bf16_t* A, const bf16_t* Bt, int K, const Epi& E) {
;     ...
;             for (int kb = 0; kb < nkb; kb += 2) {
;                 if (kb + 1 < nkb) SG_LOAD(kb + 1, 1);
; #pragma unroll
;                 for (int k4 = 0; k4 < 4; ++k4)
; #pragma unroll
;                     for (int jn = 0; jn < NTW; ++jn) acc[jn] = MFMA16(Bf[0][k4][jn], Af[0][k4], acc[jn]);
;                 if (kb + 1 < nkb) {
;                     if (kb + 2 < nkb) SG_LOAD(kb + 2, 0);
; #pragma unroll
;                     for (int k4 = 0; k4 < 4; ++k4)
; #pragma unroll
;                         for (int jn = 0; jn < NTW; ++jn) acc[jn] = MFMA16(Bf[1][k4][jn], Af[1][k4], acc[jn]);
;                 }
;             }
	v_mfma_f32_16x16x32_bf16 v[236:239], v[136:139], v[120:123], v[236:239]
	global_load_dwordx4 v[120:123], v[0:1], off offset:704
	global_load_dwordx4 v[124:127], v[240:241], off offset:704
	global_load_dwordx4 v[128:131], v[242:243], off offset:704
	global_load_dwordx4 v[132:135], v[244:245], off offset:704
	global_load_dwordx4 v[136:139], v[246:247], off offset:704
	s_waitcnt vmcnt(38)
	v_mfma_f32_16x16x32_bf16 v[224:227], v[144:147], v[140:143], v[224:227]
	s_waitcnt vmcnt(37)
	v_mfma_f32_16x16x32_bf16 v[228:231], v[148:151], v[140:143], v[228:231]
	s_waitcnt vmcnt(36)
	v_mfma_f32_16x16x32_bf16 v[232:235], v[152:155], v[140:143], v[232:235]
	s_waitcnt vmcnt(35)
	v_mfma_f32_16x16x32_bf16 v[236:239], v[156:159], v[140:143], v[236:239]
	global_load_dwordx4 v[140:143], v[0:1], off offset:768
	global_load_dwordx4 v[144:147], v[240:241], off offset:768
	global_load_dwordx4 v[148:151], v[242:243], off offset:768
	global_load_dwordx4 v[152:155], v[244:245], off offset:768
	global_load_dwordx4 v[156:159], v[246:247], off offset:768
	s_waitcnt vmcnt(38)
	v_mfma_f32_16x16x32_bf16 v[224:227], v[164:167], v[160:163], v[224:227]
	s_waitcnt vmcnt(37)
	v_mfma_f32_16x16x32_bf16 v[228:231], v[168:171], v[160:163], v[228:231]
	s_waitcnt vmcnt(36)
	v_mfma_f32_16x16x32_bf16 v[232:235], v[172:175], v[160:163], v[232:235]
	s_waitcnt vmcnt(35)
	v_mfma_f32_16x16x32_bf16 v[236:239], v[176:179], v[160:163], v[236:239]
	global_load_dwordx4 v[160:163], v[0:1], off offset:832
	global_load_dwordx4 v[164:167], v[240:241], off offset:832
	global_load_dwordx4 v[168:171], v[242:243], off offset:832
	global_load_dwordx4 v[172:175], v[244:245], off offset:832
	global_load_dwordx4 v[176:179], v[246:247], off offset:832
	s_waitcnt vmcnt(38)
	v_mfma_f32_16x16x32_bf16 v[224:227], v[184:187], v[180:183], v[224:227]
	s_waitcnt vmcnt(37)
	v_mfma_f32_16x16x32_bf16 v[228:231], v[188:191], v[180:183], v[228:231]
	s_waitcnt vmcnt(36)
	v_mfma_f32_16x16x32_bf16 v[232:235], v[192:195], v[180:183], v[232:235]
	s_waitcnt vmcnt(35)
	v_mfma_f32_16x16x32_bf16 v[236:239], v[196:199], v[180:183], v[236:239]
	global_load_dwordx4 v[180:183], v[0:1], off offset:896
	global_load_dwordx4 v[184:187], v[240:241], off offset:896
	global_load_dwordx4 v[188:191], v[242:243], off offset:896
	global_load_dwordx4 v[192:195], v[244:245], off offset:896
	global_load_dwordx4 v[196:199], v[246:247], off offset:896
	s_waitcnt vmcnt(38)
	v_mfma_f32_16x16x32_bf16 v[224:227], v[206:209], v[202:205], v[224:227]
	s_waitcnt vmcnt(37)
	v_mfma_f32_16x16x32_bf16 v[228:231], v[210:213], v[202:205], v[228:231]
	s_waitcnt vmcnt(36)
	v_mfma_f32_16x16x32_bf16 v[232:235], v[214:217], v[202:205], v[232:235]
	s_waitcnt vmcnt(35)
	v_mfma_f32_16x16x32_bf16 v[236:239], v[218:221], v[202:205], v[236:239]
	global_load_dwordx4 v[202:205], v[0:1], off offset:960
	global_load_dwordx4 v[206:209], v[240:241], off offset:960
	global_load_dwordx4 v[210:213], v[242:243], off offset:960
	global_load_dwordx4 v[214:217], v[244:245], off offset:960
	global_load_dwordx4 v[218:221], v[246:247], off offset:960
	s_waitcnt vmcnt(38)
	v_mfma_f32_16x16x32_bf16 v[224:227], v[64:67], v[60:63], v[224:227]
	s_waitcnt vmcnt(37)
	v_mfma_f32_16x16x32_bf16 v[228:231], v[68:71], v[60:63], v[228:231]
	s_waitcnt vmcnt(36)
	v_mfma_f32_16x16x32_bf16 v[232:235], v[72:75], v[60:63], v[232:235]
	s_waitcnt vmcnt(35)
	v_mfma_f32_16x16x32_bf16 v[236:239], v[76:79], v[60:63], v[236:239]
	s_waitcnt vmcnt(33)
	v_mfma_f32_16x16x32_bf16 v[224:227], v[84:87], v[80:83], v[224:227]
	s_waitcnt vmcnt(32)
	v_mfma_f32_16x16x32_bf16 v[228:231], v[88:91], v[80:83], v[228:231]
	s_waitcnt vmcnt(31)
	v_mfma_f32_16x16x32_bf16 v[232:235], v[92:95], v[80:83], v[232:235]
	s_waitcnt vmcnt(30)
	v_mfma_f32_16x16x32_bf16 v[236:239], v[96:99], v[80:83], v[236:239]
	s_waitcnt vmcnt(28)
	v_mfma_f32_16x16x32_bf16 v[224:227], v[104:107], v[100:103], v[224:227]
	s_waitcnt vmcnt(27)
	v_mfma_f32_16x16x32_bf16 v[228:231], v[108:111], v[100:103], v[228:231]
	s_waitcnt vmcnt(26)
	v_mfma_f32_16x16x32_bf16 v[232:235], v[112:115], v[100:103], v[232:235]
	s_waitcnt vmcnt(25)
	v_mfma_f32_16x16x32_bf16 v[236:239], v[116:119], v[100:103], v[236:239]
	s_waitcnt vmcnt(23)
	v_mfma_f32_16x16x32_bf16 v[224:227], v[124:127], v[120:123], v[224:227]
	s_waitcnt vmcnt(22)
	v_mfma_f32_16x16x32_bf16 v[228:231], v[128:131], v[120:123], v[228:231]
	s_waitcnt vmcnt(21)
	v_mfma_f32_16x16x32_bf16 v[232:235], v[132:135], v[120:123], v[232:235]
	s_waitcnt vmcnt(20)
	v_mfma_f32_16x16x32_bf16 v[236:239], v[136:139], v[120:123], v[236:239]
	s_waitcnt vmcnt(18)
	v_mfma_f32_16x16x32_bf16 v[224:227], v[144:147], v[140:143], v[224:227]
	s_waitcnt vmcnt(17)
	v_mfma_f32_16x16x32_bf16 v[228:231], v[148:151], v[140:143], v[228:231]
	s_waitcnt vmcnt(16)
	v_mfma_f32_16x16x32_bf16 v[232:235], v[152:155], v[140:143], v[232:235]
	s_waitcnt vmcnt(15)
	v_mfma_f32_16x16x32_bf16 v[236:239], v[156:159], v[140:143], v[236:239]
	s_waitcnt vmcnt(13)
	v_mfma_f32_16x16x32_bf16 v[224:227], v[164:167], v[160:163], v[224:227]
	s_waitcnt vmcnt(12)
	v_mfma_f32_16x16x32_bf16 v[228:231], v[168:171], v[160:163], v[228:231]
	s_waitcnt vmcnt(11)
	v_mfma_f32_16x16x32_bf16 v[232:235], v[172:175], v[160:163], v[232:235]
	s_waitcnt vmcnt(10)
	v_mfma_f32_16x16x32_bf16 v[236:239], v[176:179], v[160:163], v[236:239]
	s_waitcnt vmcnt(8)
	v_mfma_f32_16x16x32_bf16 v[224:227], v[184:187], v[180:183], v[224:227]
	s_waitcnt vmcnt(7)
	v_mfma_f32_16x16x32_bf16 v[228:231], v[188:191], v[180:183], v[228:231]
	s_waitcnt vmcnt(6)
	v_mfma_f32_16x16x32_bf16 v[232:235], v[192:195], v[180:183], v[232:235]
	s_waitcnt vmcnt(5)
	v_mfma_f32_16x16x32_bf16 v[236:239], v[196:199], v[180:183], v[236:239]
	s_waitcnt vmcnt(3)
	v_mfma_f32_16x16x32_bf16 v[224:227], v[206:209], v[202:205], v[224:227]
	s_waitcnt vmcnt(2)
	v_mfma_f32_16x16x32_bf16 v[228:231], v[210:213], v[202:205], v[228:231]
	s_waitcnt vmcnt(1)
	v_mfma_f32_16x16x32_bf16 v[232:235], v[214:217], v[202:205], v[232:235]
	s_waitcnt vmcnt(0)
	v_mfma_f32_16x16x32_bf16 v[236:239], v[218:221], v[202:205], v[236:239]
	s_and_saveexec_b64 s[2:3], s[6:7]
	s_cbranch_execz .LsgB_b
; #define LAS __attribute__((address_space(3)))
; #define LDS_BARRIER() asm volatile("s_waitcnt lgkmcnt(0)\n\ts_barrier" ::: "memory")
;     __device__ __forceinline__ Pre pre(int row, int col) const { return Pre{rstd32(rsqs + row * 32)}; }
; __device__ __forceinline__ float rstd32(const float* p) {
;     f32x4 s = ((const f32x4*)p)[0];
; #pragma unroll
;     for (int i = 1; i < 8; ++i) s += ((const f32x4*)p)[i];
;     return rsqrtf(((s[0] + s[1]) + (s[2] + s[3])) * (1.0f / D) + EPS);
; }
; template <class Epi, int N>
; __device__ __forceinline__ void sgemm16(Frame& F0, const bf16_t* A, const bf16_t* Bt, int K, const Epi& E) {
;     ...
;         for (int jn = 0; jn < NTW; ++jn) *(LAS f32x4*)(lds + ((size_t)((ksi * 16 + fr) * CW + (ng * NTW + jn) * 16 + 4 * fq)) * 4) = acc[jn];
;         LDS_BARRIER();
;         if (eact) {
;             f32x4 s0 = (f32x4){0.f, 0.f, 0.f, 0.f}, s1 = s0;
; #pragma unroll
;             for (int kk = 0; kk < KS; ++kk) { const LAS f32x4* p = (const LAS f32x4*)(lds + ((size_t)((kk * 16 + erow) * CW + 8 * ecg)) * 4); s0 += p[0]; s1 += p[1]; }
;             E(16 * F.xq + erow, slot, slot * CW + 8 * ecg, s0, s1, pre);
;         }
;         LDS_BARRIER();
;     }
; }
;     __device__ __forceinline__ Pre pre(int row, int col) const { return Pre{rstd32(rsqs + row * 32)}; }
;     __device__ __forceinline__ void operator()(int row, int strip, int col, f32x4 s0, f32x4 s1, const Pre& p) const {
;         const int oc0 = mode == 0 ? src_even(col) : src_odd(col), oc1 = mode == 0 ? src_even(col + 4) : src_odd(col + 4);
;         float* q = SZ + (size_t)row * ldz; *(f32x4*)(q + oc0) = s0 * p.rs; *(f32x4*)(q + oc1) = s1 * p.rs;
	s_mov_b32 s0, 0x800000
	v_pk_add_f32 v[30:31], v[30:31], v[34:35]
	v_pk_add_f32 v[28:29], v[28:29], v[32:33]
	v_pk_add_f32 v[30:31], v[30:31], v[38:39]
	v_pk_add_f32 v[28:29], v[28:29], v[36:37]
	v_pk_add_f32 v[30:31], v[30:31], v[42:43]
	v_pk_add_f32 v[28:29], v[28:29], v[40:41]
	v_pk_add_f32 v[30:31], v[30:31], v[46:47]
	v_pk_add_f32 v[28:29], v[28:29], v[44:45]
	v_pk_add_f32 v[30:31], v[30:31], v[50:51]
	v_pk_add_f32 v[28:29], v[28:29], v[48:49]
	v_pk_add_f32 v[30:31], v[30:31], v[54:55]
	v_pk_add_f32 v[28:29], v[28:29], v[52:53]
	v_pk_add_f32 v[30:31], v[30:31], v[58:59]
	v_pk_add_f32 v[28:29], v[28:29], v[56:57]
	s_nop 0
	v_pk_mov_b32 v[32:33], v[28:29], v[30:31] op_sel:[1,0]
	v_mov_b32_e32 v29, v31
	v_pk_add_f32 v[28:29], v[32:33], v[28:29]
	s_nop 0
	v_add_f32_e32 v8, v28, v29
	v_mov_b32_e32 v34, 0x358637bd
	v_fmamk_f32 v8, v8, 0x3a800000, v34
	v_cmp_gt_f32_e32 vcc, s0, v8
	v_mul_f32_e32 v34, 0x4b800000, v8
	s_nop 0
	v_cndmask_b32_e32 v8, v8, v34, vcc
	v_rsq_f32_e32 v8, v8
	s_nop 0
	v_mul_f32_e32 v34, 0x45800000, v8
	v_cndmask_b32_e32 v8, v8, v34, vcc
.LsgB_b:
	s_or_b64 exec, exec, s[2:3]
	s_nop 7
	ds_write_b128 v25, v[224:227]
	ds_write_b128 v25, v[228:231] offset:64
	ds_write_b128 v25, v[232:235] offset:128
	ds_write_b128 v25, v[236:239] offset:192
	s_waitcnt lgkmcnt(0)
	s_barrier
	s_and_saveexec_b64 s[2:3], s[6:7]
	s_cbranch_execz .LBB0_789
	ds_read_b128 v[10:13], v26
	ds_read_b128 v[14:17], v26 offset:16
	s_waitcnt lgkmcnt(0)
	v_pk_add_f32 v[28:29], v[12:13], 0 op_sel_hi:[1,0]
	v_pk_add_f32 v[30:31], v[10:11], 0 op_sel_hi:[1,0]
	ds_read_b128 v[10:13], v26 offset:16384
	v_pk_add_f32 v[14:15], v[14:15], 0 op_sel_hi:[1,0]
	v_pk_add_f32 v[16:17], v[16:17], 0 op_sel_hi:[1,0]
	s_waitcnt lgkmcnt(0)
	v_pk_add_f32 v[28:29], v[28:29], v[12:13]
	v_pk_add_f32 v[30:31], v[30:31], v[10:11]
	ds_read_b128 v[10:13], v26 offset:16400
	s_waitcnt lgkmcnt(0)
	v_pk_add_f32 v[14:15], v[14:15], v[10:11]
	v_add_u32_e32 v10, v18, v23
	v_ashrrev_i32_e32 v10, 2, v10
	v_and_b32_e32 v10, 0xffffffc0, v10
	v_add_u32_e32 v32, v10, v19
	v_add_u32_e32 v34, v20, v10
	v_ashrrev_i32_e32 v33, 31, v32
	v_pk_add_f32 v[16:17], v[16:17], v[12:13]
	v_pk_mul_f32 v[12:13], v[8:9], v[28:29] op_sel_hi:[0,1]
	v_pk_mul_f32 v[10:11], v[8:9], v[30:31] op_sel_hi:[0,1]
	v_lshl_add_u64 v[28:29], v[32:33], 2, v[6:7]
	v_ashrrev_i32_e32 v35, 31, v34
	global_store_dwordx4 v[28:29], v[10:13], off
	s_nop 1
	v_pk_mul_f32 v[12:13], v[8:9], v[16:17] op_sel_hi:[0,1]
	v_pk_mul_f32 v[10:11], v[8:9], v[14:15] op_sel_hi:[0,1]
	v_lshl_add_u64 v[14:15], v[34:35], 2, v[6:7]
	global_store_dwordx4 v[14:15], v[10:13], off
	s_branch .LBB0_789
